# attention tile loops: all K/Q fragment LDS reads of the QK section issued ahead of the MFMAs, one register group per fragment
# baseline (speedup 1.0000x reference)
.LBB0_634:
	s_lshl_b32 s0, 1, s0
	s_waitcnt vmcnt(0)
	v_and_b32_e32 v0, s0, v187
	v_and_b32_e32 v66, s0, v188
	v_cmp_ne_u32_e64 s[6:7], 0, v0
	v_cmp_ne_u32_e32 vcc, 0, v66
	v_cmp_le_u32_e64 s[8:9], s85, v143
	v_cmp_le_u32_e64 s[2:3], s85, v177
	s_and_b64 s[8:9], s[8:9], s[6:7]
	s_and_b64 s[2:3], s[2:3], vcc
	s_cmp_lg_u64 s[8:9], 0
	s_cselect_b64 s[8:9], -1, 0
	s_cmp_lg_u64 s[2:3], 0
	s_cselect_b64 s[2:3], -1, 0
	v_cndmask_b32_e64 v0, 0, 1, s[8:9]
	v_cndmask_b32_e64 v167, 0, 1, s[2:3]
	s_or_b64 s[0:1], s[8:9], s[2:3]
	s_and_saveexec_b64 s[54:55], s[0:1]
	s_cbranch_execz .LBB0_646
	s_cmp_eq_u32 s87, 0
	s_cselect_b64 s[58:59], -1, 0
	s_and_b64 s[0:1], s[58:59], exec
	s_cselect_b32 s0, 0, 0x2400
	v_add_u32_e32 v168, s0, v178
	ds_read_b128 v[158:161], v168
	ds_read_b128 v[162:165], v176 offset:53248
	ds_read_b128 v[206:209], v176 offset:57344
	ds_read_b128 v[218:221], v168 offset:4608
	v_cmp_gt_i32_e64 s[4:5], s85, v190
	s_waitcnt lgkmcnt(4)
	v_cndmask_b32_e64 v66, v173, v189, s[6:7]
	v_cndmask_b32_e64 v166, 0, v171, s[4:5]
	v_cndmask_b32_e64 v66, v66, 0, s[4:5]
	v_cndmask_b32_e32 v67, v173, v189, vcc
	v_cmp_gt_i32_e64 s[4:5], s85, v191
	v_cndmask_b32_e64 v240, v173, v66, s[8:9]
	s_nop 0
	v_cndmask_b32_e64 v67, v67, 0, s[4:5]
	s_nop 1
	v_cndmask_b32_e64 v241, v173, v67, s[2:3]
	ds_read_b128 v[196:199], v168 offset:32
	ds_read_b128 v[202:205], v176 offset:54272
	ds_read_b128 v[210:213], v176 offset:58368
	ds_read_b128 v[214:217], v168 offset:4640
	ds_read_b128 v[222:225], v168 offset:64
	ds_read_b128 v[242:245], v176 offset:55296
	ds_read_b128 v[246:249], v176 offset:59392
	ds_read_b128 v[230:233], v168 offset:4672
	s_waitcnt lgkmcnt(10)
	v_mfma_f32_32x32x16_bf16 v[98:113], v[158:161], v[162:165], 0
	s_waitcnt lgkmcnt(9)
	v_mfma_f32_32x32x16_bf16 v[114:129], v[158:161], v[206:209], 0
	s_waitcnt lgkmcnt(8)
	v_mfma_f32_32x32x16_bf16 v[82:97], v[218:221], v[162:165], 0
	v_mfma_f32_32x32x16_bf16 v[66:81], v[218:221], v[206:209], 0
	ds_read_b128 v[226:229], v168 offset:96
	ds_read_b128 v[250:253], v176 offset:56320
	ds_read_b128 v[162:165], v176 offset:60416
	ds_read_b128 v[234:237], v168 offset:4704
	s_waitcnt lgkmcnt(10)
	v_mfma_f32_32x32x16_bf16 v[98:113], v[196:199], v[202:205], v[98:113]
	s_waitcnt lgkmcnt(9)
	v_mfma_f32_32x32x16_bf16 v[114:129], v[196:199], v[210:213], v[114:129]
	s_waitcnt lgkmcnt(8)
	v_mfma_f32_32x32x16_bf16 v[82:97], v[214:217], v[202:205], v[82:97]
	v_mfma_f32_32x32x16_bf16 v[66:81], v[214:217], v[210:213], v[66:81]
	s_waitcnt lgkmcnt(6)
	v_mfma_f32_32x32x16_bf16 v[98:113], v[222:225], v[242:245], v[98:113]
	s_waitcnt lgkmcnt(5)
	v_mfma_f32_32x32x16_bf16 v[114:129], v[222:225], v[246:249], v[114:129]
	s_waitcnt lgkmcnt(4)
	v_mfma_f32_32x32x16_bf16 v[82:97], v[230:233], v[242:245], v[82:97]
	v_mfma_f32_32x32x16_bf16 v[66:81], v[230:233], v[246:249], v[66:81]
	s_waitcnt lgkmcnt(2)
	v_mfma_f32_32x32x16_bf16 v[98:113], v[226:229], v[250:253], v[98:113]
	s_waitcnt lgkmcnt(1)
	v_mfma_f32_32x32x16_bf16 v[114:129], v[226:229], v[162:165], v[114:129]
	v_cndmask_b32_e64 v158, 0, v172, s[6:7]
	v_or3_b32 v0, v158, v166, v0
	v_cndmask_b32_e64 v158, v158, v0, s[8:9]
	v_and_b32_e32 v0, 0x100, v158
	v_cmp_ne_u32_e64 s[6:7], 0, v0
	v_add_u32_e32 v0, s60, v192
	s_waitcnt lgkmcnt(0)
	v_mfma_f32_32x32x16_bf16 v[82:97], v[234:237], v[250:253], v[82:97]
	v_mfma_f32_32x32x16_bf16 v[66:81], v[234:237], v[162:165], v[66:81]
	s_and_saveexec_b64 s[8:9], s[6:7]
	s_cbranch_execz .LBB0_641
	v_lshl_add_u32 v206, v0, 2, s92
	v_and_b32_e32 v205, 0x10000, v158
	v_cmp_ne_u32_e64 s[6:7], 0, v205
	v_mov_b32_e32 v207, s93
	s_nop 1
	v_cndmask_b32_e64 v206, v207, v206, s[6:7]
	ds_read2_b32 v[208:209], v206 offset0:59 offset1:58
	ds_read2_b32 v[210:211], v206 offset0:57 offset1:56
	ds_read2_b32 v[212:213], v206 offset0:51 offset1:50
	ds_read2_b32 v[214:215], v206 offset0:49 offset1:48
	ds_read2_b32 v[216:217], v206 offset0:43 offset1:42
	ds_read2_b32 v[218:219], v206 offset0:41 offset1:40
	ds_read2_b32 v[220:221], v206 offset0:35 offset1:34
	ds_read2_b32 v[222:223], v206 offset0:33 offset1:32
	ds_read2_b32 v[224:225], v206 offset0:27 offset1:26
	ds_read2_b32 v[226:227], v206 offset0:25 offset1:24
	ds_read2_b32 v[228:229], v206 offset0:19 offset1:18
	ds_read2_b32 v[230:231], v206 offset0:17 offset1:16
	ds_read2_b32 v[232:233], v206 offset0:11 offset1:10
	ds_read2_b32 v[234:235], v206 offset0:9 offset1:8
	ds_read2_b32 v[236:237], v206 offset0:3 offset1:2
	ds_read2_b32 v[238:239], v206 offset0:1 offset1:0
	s_waitcnt lgkmcnt(8)
	v_pk_add_f32 v[98:99], v[98:99], v[208:209]
	v_pk_add_f32 v[100:101], v[100:101], v[210:211]
	v_pk_add_f32 v[102:103], v[102:103], v[212:213]
	v_pk_add_f32 v[104:105], v[104:105], v[214:215]
	v_pk_add_f32 v[106:107], v[106:107], v[216:217]
	v_pk_add_f32 v[108:109], v[108:109], v[218:219]
	v_pk_add_f32 v[110:111], v[110:111], v[220:221]
	v_pk_add_f32 v[112:113], v[112:113], v[222:223]
	s_waitcnt lgkmcnt(0)
	v_pk_add_f32 v[82:83], v[82:83], v[224:225]
	v_pk_add_f32 v[84:85], v[84:85], v[226:227]
	v_pk_add_f32 v[86:87], v[86:87], v[228:229]
	v_pk_add_f32 v[88:89], v[88:89], v[230:231]
	v_pk_add_f32 v[90:91], v[90:91], v[232:233]
	v_pk_add_f32 v[92:93], v[92:93], v[234:235]
	v_pk_add_f32 v[94:95], v[94:95], v[236:237]
	v_pk_add_f32 v[96:97], v[96:97], v[238:239]

.LBB0_655:
	s_add_i32 s0, s84, 63
	v_cmp_le_u32_e32 vcc, s84, v143
	v_cmp_ge_i32_e64 s[2:3], s0, v168
	s_and_b64 s[2:3], vcc, s[2:3]
	v_cmp_le_u32_e32 vcc, s84, v177
	v_cmp_ge_i32_e64 s[4:5], s0, v169
	s_and_b64 vcc, vcc, s[4:5]
	s_or_b64 s[4:5], s[2:3], vcc
	s_and_saveexec_b64 s[60:61], s[4:5]
	s_cbranch_execz .LBB0_663
	v_cmp_gt_i32_e64 s[4:5], s0, v182
	v_cmp_lt_i32_e64 s[6:7], s84, v183
	v_cmp_gt_i32_e64 s[8:9], s0, v167
	v_cmp_lt_i32_e64 s[10:11], s84, v185
	s_or_b64 s[6:7], s[4:5], s[6:7]
	s_or_b64 s[8:9], s[8:9], s[10:11]
	s_cmp_eq_u32 s86, 0
	s_cselect_b64 s[4:5], -1, 0
	s_and_b64 s[0:1], s[4:5], exec
	s_waitcnt lgkmcnt(0)
	v_cndmask_b32_e64 v0, v184, 0, s[6:7]
	v_cndmask_b32_e64 v66, v184, 0, s[8:9]
	s_cselect_b32 s0, 0, 0x2400
	v_cndmask_b32_e64 v244, v173, v66, s[2:3]
	v_cndmask_b32_e32 v245, v173, v0, vcc
	v_add_u32_e32 v0, s0, v178
	ds_read_b128 v[156:159], v0
	ds_read_b128 v[160:163], v176 offset:53248
	ds_read_b128 v[196:199], v176 offset:57344
	ds_read_b128 v[228:231], v0 offset:4608
	ds_read_b128 v[188:191], v0 offset:32
	ds_read_b128 v[192:195], v176 offset:54272
	ds_read_b128 v[202:205], v176 offset:58368
	ds_read_b128 v[206:209], v0 offset:4640
	ds_read_b128 v[232:235], v0 offset:64
	ds_read_b128 v[240:243], v176 offset:55296
	ds_read_b128 v[246:249], v176 offset:59392
	ds_read_b128 v[236:239], v0 offset:4672
	s_waitcnt lgkmcnt(10)
	v_mfma_f32_32x32x16_bf16 v[98:113], v[156:159], v[160:163], 0
	s_and_b64 s[0:1], s[2:3], s[8:9]
	s_waitcnt lgkmcnt(9)
	v_mfma_f32_32x32x16_bf16 v[114:129], v[156:159], v[196:199], 0
	s_waitcnt lgkmcnt(8)
	v_mfma_f32_32x32x16_bf16 v[82:97], v[228:231], v[160:163], 0
	v_mfma_f32_32x32x16_bf16 v[66:81], v[228:231], v[196:199], 0
	ds_read_b128 v[212:215], v0 offset:96
	ds_read_b128 v[216:219], v176 offset:56320
	ds_read_b128 v[220:223], v176 offset:60416
	ds_read_b128 v[224:227], v0 offset:4704
	s_waitcnt lgkmcnt(10)
	v_mfma_f32_32x32x16_bf16 v[98:113], v[188:191], v[192:195], v[98:113]
	s_waitcnt lgkmcnt(9)
	v_mfma_f32_32x32x16_bf16 v[114:129], v[188:191], v[202:205], v[114:129]
	s_waitcnt lgkmcnt(8)
	v_mfma_f32_32x32x16_bf16 v[82:97], v[206:209], v[192:195], v[82:97]
	v_mfma_f32_32x32x16_bf16 v[66:81], v[206:209], v[202:205], v[66:81]
	s_waitcnt lgkmcnt(6)
	v_mfma_f32_32x32x16_bf16 v[98:113], v[232:235], v[240:243], v[98:113]
	s_waitcnt lgkmcnt(5)
	v_mfma_f32_32x32x16_bf16 v[114:129], v[232:235], v[246:249], v[114:129]
	s_waitcnt lgkmcnt(4)
	v_mfma_f32_32x32x16_bf16 v[82:97], v[236:239], v[240:243], v[82:97]
	v_mfma_f32_32x32x16_bf16 v[66:81], v[236:239], v[246:249], v[66:81]
	s_waitcnt lgkmcnt(2)
	v_mfma_f32_32x32x16_bf16 v[98:113], v[212:215], v[216:219], v[98:113]
	s_waitcnt lgkmcnt(1)
	v_mfma_f32_32x32x16_bf16 v[114:129], v[212:215], v[220:223], v[114:129]
	s_waitcnt lgkmcnt(0)
	v_mfma_f32_32x32x16_bf16 v[82:97], v[224:227], v[216:219], v[82:97]
	v_mfma_f32_32x32x16_bf16 v[66:81], v[224:227], v[220:223], v[66:81]
	s_and_saveexec_b64 s[8:9], s[0:1]
	s_cbranch_execz .LBB0_658
	v_lshl_add_u32 v211, v181, 2, s95
	ds_read2_b32 v[212:213], v211 offset0:59 offset1:58
	ds_read2_b32 v[214:215], v211 offset0:57 offset1:56
	ds_read2_b32 v[216:217], v211 offset0:51 offset1:50
	ds_read2_b32 v[218:219], v211 offset0:49 offset1:48
	ds_read2_b32 v[220:221], v211 offset0:43 offset1:42
	ds_read2_b32 v[222:223], v211 offset0:41 offset1:40
	ds_read2_b32 v[224:225], v211 offset0:35 offset1:34
	ds_read2_b32 v[226:227], v211 offset0:33 offset1:32
	ds_read2_b32 v[228:229], v211 offset0:27 offset1:26
	ds_read2_b32 v[230:231], v211 offset0:25 offset1:24
	ds_read2_b32 v[232:233], v211 offset0:19 offset1:18
	ds_read2_b32 v[234:235], v211 offset0:17 offset1:16
	ds_read2_b32 v[236:237], v211 offset0:11 offset1:10
	ds_read2_b32 v[238:239], v211 offset0:9 offset1:8
	ds_read2_b32 v[240:241], v211 offset0:3 offset1:2
	ds_read2_b32 v[242:243], v211 offset0:1 offset1:0
	s_waitcnt lgkmcnt(8)
	v_pk_add_f32 v[98:99], v[98:99], v[212:213]
	v_pk_add_f32 v[100:101], v[100:101], v[214:215]
	v_pk_add_f32 v[102:103], v[102:103], v[216:217]
	v_pk_add_f32 v[104:105], v[104:105], v[218:219]
	v_pk_add_f32 v[106:107], v[106:107], v[220:221]
	v_pk_add_f32 v[108:109], v[108:109], v[222:223]
	v_pk_add_f32 v[110:111], v[110:111], v[224:225]
	v_pk_add_f32 v[112:113], v[112:113], v[226:227]
	s_waitcnt lgkmcnt(0)
	v_pk_add_f32 v[82:83], v[82:83], v[228:229]
	v_pk_add_f32 v[84:85], v[84:85], v[230:231]
	v_pk_add_f32 v[86:87], v[86:87], v[232:233]
	v_pk_add_f32 v[88:89], v[88:89], v[234:235]
	v_pk_add_f32 v[90:91], v[90:91], v[236:237]
	v_pk_add_f32 v[92:93], v[92:93], v[238:239]
	v_pk_add_f32 v[94:95], v[94:95], v[240:241]
	v_pk_add_f32 v[96:97], v[96:97], v[242:243]

.LBB0_1326:
	s_lshr_b32 s0, s0, 2
	s_lshl_b32 s0, 1, s0
	v_and_b32_e32 v64, s0, v205
	v_and_b32_e32 v65, s0, v175
	v_cmp_ne_u32_e64 s[4:5], 0, v64
	v_cmp_ne_u32_e32 vcc, 0, v65
	v_cmp_le_i32_e64 s[6:7], s18, v206
	v_cmp_le_i32_e64 s[2:3], s18, v207
	s_and_b64 s[6:7], s[6:7], s[4:5]
	s_and_b64 s[2:3], s[2:3], vcc
	s_cmp_lg_u64 s[6:7], 0
	s_cselect_b64 s[6:7], -1, 0
	s_cmp_lg_u64 s[2:3], 0
	s_cselect_b64 s[2:3], -1, 0
	v_cndmask_b32_e64 v64, 0, 1, s[6:7]
	v_cndmask_b32_e64 v168, 0, 1, s[2:3]
	s_or_b64 s[0:1], s[6:7], s[2:3]
	s_and_saveexec_b64 s[12:13], s[0:1]
	s_cbranch_execz .LBB0_1338
	v_add_u32_e32 v65, s19, v208
	v_subrev_u32_e32 v66, 63, v65
	v_cmp_gt_i32_e64 s[8:9], s87, v66
	v_cndmask_b32_e64 v215, 0, v202, s[4:5]
	s_cmp_eq_u32 s97, 0
	v_cndmask_b32_e64 v66, 0, v198, s[8:9]
	v_or3_b32 v216, v215, v66, v64
	s_waitcnt lgkmcnt(8)
	v_cndmask_b32_e64 v64, v203, v212, s[4:5]
	v_cndmask_b32_e64 v64, v64, 0, s[8:9]
	s_cselect_b64 s[8:9], -1, 0
	s_and_b64 s[0:1], s[8:9], exec
	s_cselect_b32 s0, 0, 0x2400
	v_subrev_u32_e32 v65, 31, v65
	v_add_u32_e32 v217, s0, v209
	v_cmp_gt_i32_e64 s[4:5], s87, v65
	v_cndmask_b32_e32 v65, v203, v212, vcc
	ds_read_b128 v[190:193], v217
	ds_read_b128 v[186:189], v217 offset:4608
	v_cndmask_b32_e64 v65, v65, 0, s[4:5]
	v_cndmask_b32_e64 v252, v203, v64, s[6:7]
	v_cndmask_b32_e64 v253, v203, v65, s[2:3]
	ds_read_b128 v[194:197], v217 offset:32
	ds_read_b128 v[236:239], v217 offset:4640
	ds_read_b128 v[240:243], v217 offset:64
	ds_read_b128 v[244:247], v217 offset:4672
	s_waitcnt lgkmcnt(5)
	v_mfma_f32_32x32x16_bf16 v[96:111], v[190:193], v[128:131], 0
	v_mfma_f32_32x32x16_bf16 v[112:127], v[190:193], v[148:151], 0
	s_waitcnt lgkmcnt(4)
	v_mfma_f32_32x32x16_bf16 v[80:95], v[186:189], v[128:131], 0
	v_mfma_f32_32x32x16_bf16 v[64:79], v[186:189], v[148:151], 0
	ds_read_b128 v[248:251], v217 offset:96
	ds_read_b128 v[190:193], v217 offset:4704
	s_waitcnt lgkmcnt(5)
	v_mfma_f32_32x32x16_bf16 v[96:111], v[194:197], v[132:135], v[96:111]
	v_mfma_f32_32x32x16_bf16 v[112:127], v[194:197], v[140:143], v[112:127]
	s_waitcnt lgkmcnt(4)
	v_mfma_f32_32x32x16_bf16 v[80:95], v[236:239], v[132:135], v[80:95]
	v_mfma_f32_32x32x16_bf16 v[64:79], v[236:239], v[140:143], v[64:79]
	s_waitcnt lgkmcnt(3)
	v_mfma_f32_32x32x16_bf16 v[96:111], v[240:243], v[136:139], v[96:111]
	v_mfma_f32_32x32x16_bf16 v[112:127], v[240:243], v[144:147], v[112:127]
	s_waitcnt lgkmcnt(2)
	v_mfma_f32_32x32x16_bf16 v[80:95], v[244:247], v[136:139], v[80:95]
	v_mfma_f32_32x32x16_bf16 v[64:79], v[244:247], v[144:147], v[64:79]
	s_waitcnt lgkmcnt(1)
	v_mfma_f32_32x32x16_bf16 v[96:111], v[248:251], v[152:155], v[96:111]
	v_mfma_f32_32x32x16_bf16 v[112:127], v[248:251], v[156:159], v[112:127]
	v_cndmask_b32_e64 v186, v215, v216, s[6:7]
	v_and_b32_e32 v187, 0x100, v186
	v_cmp_ne_u32_e64 s[6:7], 0, v187
	s_waitcnt lgkmcnt(0)
	v_mfma_f32_32x32x16_bf16 v[80:95], v[190:193], v[152:155], v[80:95]
	v_mfma_f32_32x32x16_bf16 v[64:79], v[190:193], v[156:159], v[64:79]
	v_add_u32_e32 v190, s19, v211
	s_and_saveexec_b64 s[14:15], s[6:7]
	s_cbranch_execz .LBB0_1333
	v_lshl_add_u32 v224, v190, 2, s91
	v_and_b32_e32 v186, 0x10000, v186
	v_cmp_ne_u32_e64 s[6:7], 0, v186
	v_mov_b32_e32 v225, 0x1d000
	s_nop 1
	v_cndmask_b32_e64 v224, v225, v224, s[6:7]
	ds_read2_b32 v[226:227], v224 offset0:59 offset1:58
	ds_read2_b32 v[228:229], v224 offset0:57 offset1:56
	ds_read2_b32 v[230:231], v224 offset0:51 offset1:50
	ds_read2_b32 v[232:233], v224 offset0:49 offset1:48
	ds_read2_b32 v[234:235], v224 offset0:43 offset1:42
	ds_read2_b32 v[236:237], v224 offset0:41 offset1:40
	ds_read2_b32 v[238:239], v224 offset0:35 offset1:34
	ds_read2_b32 v[240:241], v224 offset0:33 offset1:32
	ds_read2_b32 v[242:243], v224 offset0:27 offset1:26
	ds_read2_b32 v[244:245], v224 offset0:25 offset1:24
	ds_read2_b32 v[246:247], v224 offset0:19 offset1:18
	ds_read2_b32 v[248:249], v224 offset0:17 offset1:16
	ds_read2_b32 v[250:251], v224 offset0:11 offset1:10
	s_waitcnt lgkmcnt(5)
	v_pk_add_f32 v[96:97], v[96:97], v[226:227]
	v_pk_add_f32 v[98:99], v[98:99], v[228:229]
	v_pk_add_f32 v[100:101], v[100:101], v[230:231]
	v_pk_add_f32 v[102:103], v[102:103], v[232:233]
	v_pk_add_f32 v[104:105], v[104:105], v[234:235]
	v_pk_add_f32 v[106:107], v[106:107], v[236:237]
	v_pk_add_f32 v[108:109], v[108:109], v[238:239]
	v_pk_add_f32 v[110:111], v[110:111], v[240:241]
	ds_read2_b32 v[226:227], v224 offset0:9 offset1:8
	ds_read2_b32 v[228:229], v224 offset0:3 offset1:2
	ds_read2_b32 v[230:231], v224 offset0:1 offset1:0
	s_waitcnt lgkmcnt(3)
	v_pk_add_f32 v[80:81], v[80:81], v[242:243]
	v_pk_add_f32 v[82:83], v[82:83], v[244:245]
	v_pk_add_f32 v[84:85], v[84:85], v[246:247]
	v_pk_add_f32 v[86:87], v[86:87], v[248:249]
	v_pk_add_f32 v[88:89], v[88:89], v[250:251]
	s_waitcnt lgkmcnt(0)
	v_pk_add_f32 v[90:91], v[90:91], v[226:227]
	v_pk_add_f32 v[92:93], v[92:93], v[228:229]
	v_pk_add_f32 v[94:95], v[94:95], v[230:231]
